# RG-LRU scan loops hand-rewritten: 16-step load batches instead of serialized load-wait chains
# speedup vs baseline: 1.0237x; 1.0170x over previous
; __device__ __forceinline__ float bf2f(bf16_t h) { return __uint_as_float(((unsigned)h) << 16); }
; __device__ __forceinline__ void lru_scan(unsigned char* ws, int unit, int wave, int tid_, LAS float* sm) {
;     ...
;     const size_t m0 = (size_t)b * SEQ + t0;
;     const bf16_t* lap = LA + m0 * 512 + ch; bf16_t* up = Y + m0 * 2048 + 1536 + ch; const bf16_t* gp = U1 + m0 * 1024 + 512 + ch;
;     float A = 1.f, H = 0.f;
;     for (int t = 0; t < 512; t += 16) {
;         bf16_t la[16], uu[16];
; #pragma unroll
;         for (int k = 0; k < 16; ++k) { la[k] = lap[(size_t)(t + k) * 512]; uu[k] = up[(size_t)(t + k) * 2048]; }
; #pragma unroll
;         for (int k = 0; k < 16; ++k) { const float a = __expf(bf2f(la[k])); H = a * H + bf2f(uu[k]); A *= a; }
;     }
;     sm[wave * 64 + lane] = A; sm[512 + wave * 64 + lane] = H;
;     __syncthreads();
.LBB0_1206:
	v_readlane_b32 s0, v253, 56
	v_readlane_b32 s1, v253, 57
	s_andn2_b64 vcc, exec, s[0:1]
	s_cbranch_vccnz .LBB0_1221
	v_mov_b32_e32 v0, v234
	v_readlane_b32 s0, v253, 58
	v_and_b32_e32 v28, 63, v0
	v_mov_b32_e32 v3, 1.0
	v_or_b32_e32 v0, s0, v28
	v_readlane_b32 s0, v253, 63
	v_readlane_b32 s1, v254, 0
	s_add_u32 s6, s42, s0
	s_addc_u32 s7, s43, s1
	v_readlane_b32 s0, v253, 61
	v_readlane_b32 s1, v253, 62
	s_add_u32 s8, s42, s0
	s_addc_u32 s9, s43, s1
	v_lshlrev_b32_e32 v0, 1, v0
	v_mov_b32_e32 v6, 0
	s_mov_b32 s12, -16
	s_mov_b64 s[0:1], s[8:9]
	s_mov_b64 s[10:11], s[6:7]
	v_add_u32_e32 v64, 0x1bc00000, v0
	v_add_u32_e32 v65, 0x1000, v64
	v_add_u32_e32 v66, 0x2000, v64
	v_add_u32_e32 v67, 0x3000, v64
	v_add_u32_e32 v68, 0x7c00000, v0
	v_add_u32_e32 v69, 0x1000, v68
	v_add_u32_e32 v70, 0x2000, v68
	v_add_u32_e32 v71, 0x3000, v68
	v_add_u32_e32 v72, 0x4000, v68
	v_add_u32_e32 v73, 0x5000, v68
	v_add_u32_e32 v74, 0x6000, v68
	v_add_u32_e32 v75, 0x7000, v68
	v_add_u32_e32 v76, 0x8000, v68
	v_add_u32_e32 v77, 0x9000, v68
	v_add_u32_e32 v78, 0xa000, v68
	v_add_u32_e32 v79, 0xb000, v68
	v_add_u32_e32 v80, 0xc000, v68
	v_add_u32_e32 v81, 0xd000, v68
	v_add_u32_e32 v82, 0xe000, v68
	v_add_u32_e32 v83, 0xf000, v68
.LBB0_1208:
	global_load_ushort v32, v64, s[0:1]
	global_load_ushort v33, v64, s[0:1] offset:1024
	global_load_ushort v34, v64, s[0:1] offset:2048
	global_load_ushort v35, v64, s[0:1] offset:3072
	global_load_ushort v36, v65, s[0:1]
	global_load_ushort v37, v65, s[0:1] offset:1024
	global_load_ushort v38, v65, s[0:1] offset:2048
	global_load_ushort v39, v65, s[0:1] offset:3072
	global_load_ushort v40, v66, s[0:1]
	global_load_ushort v41, v66, s[0:1] offset:1024
	global_load_ushort v42, v66, s[0:1] offset:2048
	global_load_ushort v43, v66, s[0:1] offset:3072
	global_load_ushort v44, v67, s[0:1]
	global_load_ushort v45, v67, s[0:1] offset:1024
	global_load_ushort v46, v67, s[0:1] offset:2048
	global_load_ushort v47, v67, s[0:1] offset:3072
	global_load_ushort v48, v68, s[10:11] offset:3072
	global_load_ushort v49, v69, s[10:11] offset:3072
	global_load_ushort v50, v70, s[10:11] offset:3072
	global_load_ushort v51, v71, s[10:11] offset:3072
	global_load_ushort v52, v72, s[10:11] offset:3072
	global_load_ushort v53, v73, s[10:11] offset:3072
	global_load_ushort v54, v74, s[10:11] offset:3072
	global_load_ushort v55, v75, s[10:11] offset:3072
	global_load_ushort v56, v76, s[10:11] offset:3072
	global_load_ushort v57, v77, s[10:11] offset:3072
	global_load_ushort v58, v78, s[10:11] offset:3072
	global_load_ushort v59, v79, s[10:11] offset:3072
	global_load_ushort v60, v80, s[10:11] offset:3072
	global_load_ushort v61, v81, s[10:11] offset:3072
	global_load_ushort v62, v82, s[10:11] offset:3072
	global_load_ushort v63, v83, s[10:11] offset:3072
	s_add_u32 s0, s0, 0x4000
	s_addc_u32 s1, s1, 0
	s_add_u32 s10, s10, 0x10000
	s_addc_u32 s11, s11, 0
	s_add_i32 s12, s12, 16
	s_cmpk_lt_u32 s12, 0x1f0
	s_waitcnt vmcnt(0)
	v_lshlrev_b32_e32 v32, 16, v32
	v_lshlrev_b32_e32 v33, 16, v33
	v_lshlrev_b32_e32 v34, 16, v34
	v_lshlrev_b32_e32 v35, 16, v35
	v_lshlrev_b32_e32 v36, 16, v36
	v_lshlrev_b32_e32 v37, 16, v37
	v_lshlrev_b32_e32 v38, 16, v38
	v_lshlrev_b32_e32 v39, 16, v39
	v_lshlrev_b32_e32 v40, 16, v40
	v_lshlrev_b32_e32 v41, 16, v41
	v_lshlrev_b32_e32 v42, 16, v42
	v_lshlrev_b32_e32 v43, 16, v43
	v_lshlrev_b32_e32 v44, 16, v44
	v_lshlrev_b32_e32 v45, 16, v45
	v_lshlrev_b32_e32 v46, 16, v46
	v_lshlrev_b32_e32 v47, 16, v47
	v_mul_f32_e32 v32, 0x3fb8aa3b, v32
	v_mul_f32_e32 v33, 0x3fb8aa3b, v33
	v_mul_f32_e32 v34, 0x3fb8aa3b, v34
	v_mul_f32_e32 v35, 0x3fb8aa3b, v35
	v_mul_f32_e32 v36, 0x3fb8aa3b, v36
	v_mul_f32_e32 v37, 0x3fb8aa3b, v37
	v_mul_f32_e32 v38, 0x3fb8aa3b, v38
	v_mul_f32_e32 v39, 0x3fb8aa3b, v39
	v_mul_f32_e32 v40, 0x3fb8aa3b, v40
	v_mul_f32_e32 v41, 0x3fb8aa3b, v41
	v_mul_f32_e32 v42, 0x3fb8aa3b, v42
	v_mul_f32_e32 v43, 0x3fb8aa3b, v43
	v_mul_f32_e32 v44, 0x3fb8aa3b, v44
	v_mul_f32_e32 v45, 0x3fb8aa3b, v45
	v_mul_f32_e32 v46, 0x3fb8aa3b, v46
	v_mul_f32_e32 v47, 0x3fb8aa3b, v47
	v_exp_f32_e32 v32, v32
	v_exp_f32_e32 v33, v33
	v_exp_f32_e32 v34, v34
	v_exp_f32_e32 v35, v35
	v_exp_f32_e32 v36, v36
	v_exp_f32_e32 v37, v37
	v_exp_f32_e32 v38, v38
	v_exp_f32_e32 v39, v39
	v_exp_f32_e32 v40, v40
	v_exp_f32_e32 v41, v41
	v_exp_f32_e32 v42, v42
	v_exp_f32_e32 v43, v43
	v_exp_f32_e32 v44, v44
	v_exp_f32_e32 v45, v45
	v_exp_f32_e32 v46, v46
	v_exp_f32_e32 v47, v47
	v_lshlrev_b32_e32 v48, 16, v48
	v_lshlrev_b32_e32 v49, 16, v49
	v_lshlrev_b32_e32 v50, 16, v50
	v_lshlrev_b32_e32 v51, 16, v51
	v_lshlrev_b32_e32 v52, 16, v52
	v_lshlrev_b32_e32 v53, 16, v53
	v_lshlrev_b32_e32 v54, 16, v54
	v_lshlrev_b32_e32 v55, 16, v55
	v_lshlrev_b32_e32 v56, 16, v56
	v_lshlrev_b32_e32 v57, 16, v57
	v_lshlrev_b32_e32 v58, 16, v58
	v_lshlrev_b32_e32 v59, 16, v59
	v_lshlrev_b32_e32 v60, 16, v60
	v_lshlrev_b32_e32 v61, 16, v61
	v_lshlrev_b32_e32 v62, 16, v62
	v_lshlrev_b32_e32 v63, 16, v63
	v_fma_f32 v6, v32, v6, v48
	v_mul_f32_e32 v3, v3, v32
	v_fma_f32 v6, v33, v6, v49
	v_mul_f32_e32 v3, v3, v33
	v_fma_f32 v6, v34, v6, v50
	v_mul_f32_e32 v3, v3, v34
	v_fma_f32 v6, v35, v6, v51
	v_mul_f32_e32 v3, v3, v35
	v_fma_f32 v6, v36, v6, v52
	v_mul_f32_e32 v3, v3, v36
	v_fma_f32 v6, v37, v6, v53
	v_mul_f32_e32 v3, v3, v37
	v_fma_f32 v6, v38, v6, v54
	v_mul_f32_e32 v3, v3, v38
	v_fma_f32 v6, v39, v6, v55
	v_mul_f32_e32 v3, v3, v39
	v_fma_f32 v6, v40, v6, v56
	v_mul_f32_e32 v3, v3, v40
	v_fma_f32 v6, v41, v6, v57
	v_mul_f32_e32 v3, v3, v41
	v_fma_f32 v6, v42, v6, v58
	v_mul_f32_e32 v3, v3, v42
	v_fma_f32 v6, v43, v6, v59
	v_mul_f32_e32 v3, v3, v43
	v_fma_f32 v6, v44, v6, v60
	v_mul_f32_e32 v3, v3, v44
	v_fma_f32 v6, v45, v6, v61
	v_mul_f32_e32 v3, v3, v45
	v_fma_f32 v6, v46, v6, v62
	v_mul_f32_e32 v3, v3, v46
	v_fma_f32 v6, v47, v6, v63
	v_mul_f32_e32 v3, v3, v47
	s_cbranch_scc1 .LBB0_1208
	v_readlane_b32 s0, v253, 59
	v_mov_b32_e32 v4, 0
	s_nop 0
	v_lshl_add_u32 v2, v28, 2, s0
	v_readlane_b32 s0, v253, 38
	v_readlane_b32 s1, v253, 39
	s_andn2_b64 vcc, exec, s[0:1]
	ds_write2st64_b32 v2, v3, v6 offset1:8
	s_waitcnt lgkmcnt(0)
	s_barrier
	s_cbranch_vccnz .LBB0_1218
	v_readlane_b32 s0, v254, 30
	v_readlane_b32 s1, v254, 31
	s_andn2_b64 vcc, exec, s[0:1]
	v_readlane_b32 s1, v254, 32
	s_cbranch_vccnz .LBB0_1214
	v_lshl_add_u32 v2, v28, 2, 0
	ds_read_b32 v3, v2
	v_mov_b32_e32 v4, 0
	s_mov_b32 s0, 0

; __device__ __forceinline__ float bf2f(bf16_t h) { return __uint_as_float(((unsigned)h) << 16); }
; __device__ __forceinline__ bf16_t f2bf(float f) { return (bf16_t)(cvt_pk_bf16(f, 0.f) & 0xffffu); }
; __device__ __forceinline__ float gelu_tanh(float x) { const float u = 0.7978845608028654f * (x + 0.044715f * x * x * x); return x * sigmoidf_(2.f * u); }
; __device__ __forceinline__ void lru_scan(unsigned char* ws, int unit, int wave, int tid_, LAS float* sm) {
;     ...
;     for (int t = 0; t < 512; t += 16) {
;         bf16_t la[16], uu[16], gg[16];
; #pragma unroll
;         for (int k = 0; k < 16; ++k) { la[k] = lap[(size_t)(t + k) * 512]; uu[k] = up[(size_t)(t + k) * 2048]; gg[k] = gp[(size_t)(t + k) * 1024]; }
; #pragma unroll
;         for (int k = 0; k < 16; ++k) { const float a = __expf(bf2f(la[k])); hcar = a * hcar + bf2f(uu[k]); up[(size_t)(t + k) * 2048] = f2bf(bf2f(f2bf(hcar)) * gelu_tanh(bf2f(gg[k]))); }
;     }
.LBB0_1218:
	v_readlane_b32 s0, v255, 16
	v_readlane_b32 s1, v255, 17
	s_add_u32 s0, s42, s0
	s_addc_u32 s1, s43, s1
	s_mov_b32 s10, -16
	v_add_u32_e32 v64, 0x1bc00000, v0
	v_add_u32_e32 v65, 0x1000, v64
	v_add_u32_e32 v66, 0x2000, v64
	v_add_u32_e32 v67, 0x3000, v64
	v_add_u32_e32 v68, 0x7c00000, v0
	v_add_u32_e32 v69, 0x1000, v68
	v_add_u32_e32 v70, 0x2000, v68
	v_add_u32_e32 v71, 0x3000, v68
	v_add_u32_e32 v72, 0x4000, v68
	v_add_u32_e32 v73, 0x5000, v68
	v_add_u32_e32 v74, 0x6000, v68
	v_add_u32_e32 v75, 0x7000, v68
	v_add_u32_e32 v76, 0x8000, v68
	v_add_u32_e32 v77, 0x9000, v68
	v_add_u32_e32 v78, 0xa000, v68
	v_add_u32_e32 v79, 0xb000, v68
	v_add_u32_e32 v80, 0xc000, v68
	v_add_u32_e32 v81, 0xd000, v68
	v_add_u32_e32 v82, 0xe000, v68
	v_add_u32_e32 v83, 0xf000, v68
	v_add_u32_e32 v100, 0xfc00000, v0
	v_add_u32_e32 v101, 0x1000, v100
	v_add_u32_e32 v102, 0x2000, v100
	v_add_u32_e32 v103, 0x3000, v100
	v_add_u32_e32 v104, 0x4000, v100
	v_add_u32_e32 v105, 0x5000, v100
	v_add_u32_e32 v106, 0x6000, v100
	v_add_u32_e32 v107, 0x7000, v100
.LBB0_1219:
	global_load_ushort v32, v64, s[8:9]
	global_load_ushort v33, v64, s[8:9] offset:1024
	global_load_ushort v34, v64, s[8:9] offset:2048
	global_load_ushort v35, v64, s[8:9] offset:3072
	global_load_ushort v36, v65, s[8:9]
	global_load_ushort v37, v65, s[8:9] offset:1024
	global_load_ushort v38, v65, s[8:9] offset:2048
	global_load_ushort v39, v65, s[8:9] offset:3072
	global_load_ushort v40, v66, s[8:9]
	global_load_ushort v41, v66, s[8:9] offset:1024
	global_load_ushort v42, v66, s[8:9] offset:2048
	global_load_ushort v43, v66, s[8:9] offset:3072
	global_load_ushort v44, v67, s[8:9]
	global_load_ushort v45, v67, s[8:9] offset:1024
	global_load_ushort v46, v67, s[8:9] offset:2048
	global_load_ushort v47, v67, s[8:9] offset:3072
	global_load_ushort v48, v68, s[6:7] offset:3072
	global_load_ushort v49, v69, s[6:7] offset:3072
	global_load_ushort v50, v70, s[6:7] offset:3072
	global_load_ushort v51, v71, s[6:7] offset:3072
	global_load_ushort v52, v72, s[6:7] offset:3072
	global_load_ushort v53, v73, s[6:7] offset:3072
	global_load_ushort v54, v74, s[6:7] offset:3072
	global_load_ushort v55, v75, s[6:7] offset:3072
	global_load_ushort v56, v76, s[6:7] offset:3072
	global_load_ushort v57, v77, s[6:7] offset:3072
	global_load_ushort v58, v78, s[6:7] offset:3072
	global_load_ushort v59, v79, s[6:7] offset:3072
	global_load_ushort v60, v80, s[6:7] offset:3072
	global_load_ushort v61, v81, s[6:7] offset:3072
	global_load_ushort v62, v82, s[6:7] offset:3072
	global_load_ushort v63, v83, s[6:7] offset:3072
	global_load_ushort v84, v100, s[0:1] offset:1024
	global_load_ushort v85, v100, s[0:1] offset:3072
	global_load_ushort v86, v101, s[0:1] offset:1024
	global_load_ushort v87, v101, s[0:1] offset:3072
	global_load_ushort v88, v102, s[0:1] offset:1024
	global_load_ushort v89, v102, s[0:1] offset:3072
	global_load_ushort v90, v103, s[0:1] offset:1024
	global_load_ushort v91, v103, s[0:1] offset:3072
	global_load_ushort v92, v104, s[0:1] offset:1024
	global_load_ushort v93, v104, s[0:1] offset:3072
	global_load_ushort v94, v105, s[0:1] offset:1024
	global_load_ushort v95, v105, s[0:1] offset:3072
	global_load_ushort v96, v106, s[0:1] offset:1024
	global_load_ushort v97, v106, s[0:1] offset:3072
	global_load_ushort v98, v107, s[0:1] offset:1024
	global_load_ushort v99, v107, s[0:1] offset:3072
	s_waitcnt vmcnt(0)
	v_lshlrev_b32_e32 v32, 16, v32
	v_lshlrev_b32_e32 v33, 16, v33
	v_lshlrev_b32_e32 v34, 16, v34
	v_lshlrev_b32_e32 v35, 16, v35
	v_lshlrev_b32_e32 v36, 16, v36
	v_lshlrev_b32_e32 v37, 16, v37
	v_lshlrev_b32_e32 v38, 16, v38
	v_lshlrev_b32_e32 v39, 16, v39
	v_lshlrev_b32_e32 v40, 16, v40
	v_lshlrev_b32_e32 v41, 16, v41
	v_lshlrev_b32_e32 v42, 16, v42
	v_lshlrev_b32_e32 v43, 16, v43
	v_lshlrev_b32_e32 v44, 16, v44
	v_lshlrev_b32_e32 v45, 16, v45
	v_lshlrev_b32_e32 v46, 16, v46
	v_lshlrev_b32_e32 v47, 16, v47
	v_mul_f32_e32 v32, 0x3fb8aa3b, v32
	v_mul_f32_e32 v33, 0x3fb8aa3b, v33
	v_mul_f32_e32 v34, 0x3fb8aa3b, v34
	v_mul_f32_e32 v35, 0x3fb8aa3b, v35
	v_mul_f32_e32 v36, 0x3fb8aa3b, v36
	v_mul_f32_e32 v37, 0x3fb8aa3b, v37
	v_mul_f32_e32 v38, 0x3fb8aa3b, v38
	v_mul_f32_e32 v39, 0x3fb8aa3b, v39
	v_mul_f32_e32 v40, 0x3fb8aa3b, v40
	v_mul_f32_e32 v41, 0x3fb8aa3b, v41
	v_mul_f32_e32 v42, 0x3fb8aa3b, v42
	v_mul_f32_e32 v43, 0x3fb8aa3b, v43
	v_mul_f32_e32 v44, 0x3fb8aa3b, v44
	v_mul_f32_e32 v45, 0x3fb8aa3b, v45
	v_mul_f32_e32 v46, 0x3fb8aa3b, v46
	v_mul_f32_e32 v47, 0x3fb8aa3b, v47
	v_exp_f32_e32 v32, v32
	v_exp_f32_e32 v33, v33
	v_exp_f32_e32 v34, v34
	v_exp_f32_e32 v35, v35
	v_exp_f32_e32 v36, v36
	v_exp_f32_e32 v37, v37
	v_exp_f32_e32 v38, v38
	v_exp_f32_e32 v39, v39
	v_exp_f32_e32 v40, v40
	v_exp_f32_e32 v41, v41
	v_exp_f32_e32 v42, v42
	v_exp_f32_e32 v43, v43
	v_exp_f32_e32 v44, v44
	v_exp_f32_e32 v45, v45
	v_exp_f32_e32 v46, v46
	v_exp_f32_e32 v47, v47
	v_lshlrev_b32_e32 v48, 16, v48
	v_lshlrev_b32_e32 v49, 16, v49
	v_lshlrev_b32_e32 v50, 16, v50
	v_lshlrev_b32_e32 v51, 16, v51
	v_lshlrev_b32_e32 v52, 16, v52
	v_lshlrev_b32_e32 v53, 16, v53
	v_lshlrev_b32_e32 v54, 16, v54
	v_lshlrev_b32_e32 v55, 16, v55
	v_lshlrev_b32_e32 v56, 16, v56
	v_lshlrev_b32_e32 v57, 16, v57
	v_lshlrev_b32_e32 v58, 16, v58
	v_lshlrev_b32_e32 v59, 16, v59
	v_lshlrev_b32_e32 v60, 16, v60
	v_lshlrev_b32_e32 v61, 16, v61
	v_lshlrev_b32_e32 v62, 16, v62
	v_lshlrev_b32_e32 v63, 16, v63
	v_lshlrev_b32_e32 v84, 16, v84
	v_lshlrev_b32_e32 v85, 16, v85
	v_lshlrev_b32_e32 v86, 16, v86
	v_lshlrev_b32_e32 v87, 16, v87
	v_lshlrev_b32_e32 v88, 16, v88
	v_lshlrev_b32_e32 v89, 16, v89
	v_lshlrev_b32_e32 v90, 16, v90
	v_lshlrev_b32_e32 v91, 16, v91
; __device__ __forceinline__ float bf2f(bf16_t h) { return __uint_as_float(((unsigned)h) << 16); }
; __device__ __forceinline__ bf16_t f2bf(float f) { return (bf16_t)(cvt_pk_bf16(f, 0.f) & 0xffffu); }
; __device__ __forceinline__ float gelu_tanh(float x) { const float u = 0.7978845608028654f * (x + 0.044715f * x * x * x); return x * sigmoidf_(2.f * u); }
; __device__ __forceinline__ void lru_scan(unsigned char* ws, int unit, int wave, int tid_, LAS float* sm) {
;     ...
;         for (int k = 0; k < 16; ++k) { la[k] = lap[(size_t)(t + k) * 512]; uu[k] = up[(size_t)(t + k) * 2048]; gg[k] = gp[(size_t)(t + k) * 1024]; }
; #pragma unroll
;         for (int k = 0; k < 16; ++k) { const float a = __expf(bf2f(la[k])); hcar = a * hcar + bf2f(uu[k]); up[(size_t)(t + k) * 2048] = f2bf(bf2f(f2bf(hcar)) * gelu_tanh(bf2f(gg[k]))); }
	v_lshlrev_b32_e32 v92, 16, v92
	v_lshlrev_b32_e32 v93, 16, v93
	v_lshlrev_b32_e32 v94, 16, v94
	v_lshlrev_b32_e32 v95, 16, v95
	v_lshlrev_b32_e32 v96, 16, v96
	v_lshlrev_b32_e32 v97, 16, v97
	v_lshlrev_b32_e32 v98, 16, v98
	v_lshlrev_b32_e32 v99, 16, v99
	v_mul_f32_e32 v108, 0x3d372713, v84
	v_mul_f32_e32 v109, 0x3d372713, v85
	v_mul_f32_e32 v110, 0x3d372713, v86
	v_mul_f32_e32 v111, 0x3d372713, v87
	v_mul_f32_e32 v112, 0x3d372713, v88
	v_mul_f32_e32 v113, 0x3d372713, v89
	v_mul_f32_e32 v114, 0x3d372713, v90
	v_mul_f32_e32 v115, 0x3d372713, v91
	v_mul_f32_e32 v116, 0x3d372713, v92
	v_mul_f32_e32 v117, 0x3d372713, v93
	v_mul_f32_e32 v118, 0x3d372713, v94
	v_mul_f32_e32 v119, 0x3d372713, v95
	v_mul_f32_e32 v120, 0x3d372713, v96
	v_mul_f32_e32 v121, 0x3d372713, v97
	v_mul_f32_e32 v122, 0x3d372713, v98
	v_mul_f32_e32 v123, 0x3d372713, v99
	v_mul_f32_e32 v108, v108, v84
	v_mul_f32_e32 v109, v109, v85
	v_mul_f32_e32 v110, v110, v86
	v_mul_f32_e32 v111, v111, v87
	v_mul_f32_e32 v112, v112, v88
	v_mul_f32_e32 v113, v113, v89
	v_mul_f32_e32 v114, v114, v90
	v_mul_f32_e32 v115, v115, v91
	v_mul_f32_e32 v116, v116, v92
	v_mul_f32_e32 v117, v117, v93
	v_mul_f32_e32 v118, v118, v94
	v_mul_f32_e32 v119, v119, v95
	v_mul_f32_e32 v120, v120, v96
	v_mul_f32_e32 v121, v121, v97
	v_mul_f32_e32 v122, v122, v98
	v_mul_f32_e32 v123, v123, v99
	v_fma_f32 v108, v108, v84, v84
	v_fma_f32 v109, v109, v85, v85
	v_fma_f32 v110, v110, v86, v86
	v_fma_f32 v111, v111, v87, v87
	v_fma_f32 v112, v112, v88, v88
	v_fma_f32 v113, v113, v89, v89
	v_fma_f32 v114, v114, v90, v90
	v_fma_f32 v115, v115, v91, v91
	v_fma_f32 v116, v116, v92, v92
	v_fma_f32 v117, v117, v93, v93
	v_fma_f32 v118, v118, v94, v94
	v_fma_f32 v119, v119, v95, v95
	v_fma_f32 v120, v120, v96, v96
	v_fma_f32 v121, v121, v97, v97
	v_fma_f32 v122, v122, v98, v98
	v_fma_f32 v123, v123, v99, v99
	v_mul_f32_e32 v108, 0x3f4c422a, v108
	v_mul_f32_e32 v109, 0x3f4c422a, v109
	v_mul_f32_e32 v110, 0x3f4c422a, v110
	v_mul_f32_e32 v111, 0x3f4c422a, v111
	v_mul_f32_e32 v112, 0x3f4c422a, v112
	v_mul_f32_e32 v113, 0x3f4c422a, v113
	v_mul_f32_e32 v114, 0x3f4c422a, v114
	v_mul_f32_e32 v115, 0x3f4c422a, v115
	v_mul_f32_e32 v116, 0x3f4c422a, v116
	v_mul_f32_e32 v117, 0x3f4c422a, v117
	v_mul_f32_e32 v118, 0x3f4c422a, v118
	v_mul_f32_e32 v119, 0x3f4c422a, v119
	v_mul_f32_e32 v120, 0x3f4c422a, v120
	v_mul_f32_e32 v121, 0x3f4c422a, v121
	v_mul_f32_e32 v122, 0x3f4c422a, v122
	v_mul_f32_e32 v123, 0x3f4c422a, v123
	v_add_f32_e32 v108, v108, v108
	v_add_f32_e32 v109, v109, v109
	v_add_f32_e32 v110, v110, v110
	v_add_f32_e32 v111, v111, v111
	v_add_f32_e32 v112, v112, v112
	v_add_f32_e32 v113, v113, v113
	v_add_f32_e32 v114, v114, v114
	v_add_f32_e32 v115, v115, v115
	v_add_f32_e32 v116, v116, v116
	v_add_f32_e32 v117, v117, v117
	v_add_f32_e32 v118, v118, v118
	v_add_f32_e32 v119, v119, v119
	v_add_f32_e32 v120, v120, v120
	v_add_f32_e32 v121, v121, v121
	v_add_f32_e32 v122, v122, v122
	v_add_f32_e32 v123, v123, v123
	v_mul_f32_e32 v108, 0xbfb8aa3b, v108
	v_mul_f32_e32 v109, 0xbfb8aa3b, v109
	v_mul_f32_e32 v110, 0xbfb8aa3b, v110
	v_mul_f32_e32 v111, 0xbfb8aa3b, v111
	v_mul_f32_e32 v112, 0xbfb8aa3b, v112
	v_mul_f32_e32 v113, 0xbfb8aa3b, v113
	v_mul_f32_e32 v114, 0xbfb8aa3b, v114
	v_mul_f32_e32 v115, 0xbfb8aa3b, v115
	v_mul_f32_e32 v116, 0xbfb8aa3b, v116
	v_mul_f32_e32 v117, 0xbfb8aa3b, v117
	v_mul_f32_e32 v118, 0xbfb8aa3b, v118
	v_mul_f32_e32 v119, 0xbfb8aa3b, v119
	v_mul_f32_e32 v120, 0xbfb8aa3b, v120
	v_mul_f32_e32 v121, 0xbfb8aa3b, v121
	v_mul_f32_e32 v122, 0xbfb8aa3b, v122
	v_mul_f32_e32 v123, 0xbfb8aa3b, v123
	v_exp_f32_e32 v108, v108
	v_exp_f32_e32 v109, v109
	v_exp_f32_e32 v110, v110
	v_exp_f32_e32 v111, v111
	v_exp_f32_e32 v112, v112
	v_exp_f32_e32 v113, v113
	v_exp_f32_e32 v114, v114
	v_exp_f32_e32 v115, v115
	v_exp_f32_e32 v116, v116
	v_exp_f32_e32 v117, v117
	v_exp_f32_e32 v118, v118
	v_exp_f32_e32 v119, v119
	v_exp_f32_e32 v120, v120
	v_exp_f32_e32 v121, v121
	v_exp_f32_e32 v122, v122
	v_exp_f32_e32 v123, v123
	v_add_f32_e32 v108, 1.0, v108
	v_add_f32_e32 v109, 1.0, v109
	v_add_f32_e32 v110, 1.0, v110
	v_add_f32_e32 v111, 1.0, v111
	v_add_f32_e32 v112, 1.0, v112
	v_add_f32_e32 v113, 1.0, v113
	v_add_f32_e32 v114, 1.0, v114
	v_add_f32_e32 v115, 1.0, v115
	v_add_f32_e32 v116, 1.0, v116
	v_add_f32_e32 v117, 1.0, v117
	v_add_f32_e32 v118, 1.0, v118
	v_add_f32_e32 v119, 1.0, v119
	v_add_f32_e32 v120, 1.0, v120
	v_add_f32_e32 v121, 1.0, v121
; __device__ __forceinline__ float bf2f(bf16_t h) { return __uint_as_float(((unsigned)h) << 16); }
; __device__ __forceinline__ bf16_t f2bf(float f) { return (bf16_t)(cvt_pk_bf16(f, 0.f) & 0xffffu); }
; __device__ __forceinline__ float gelu_tanh(float x) { const float u = 0.7978845608028654f * (x + 0.044715f * x * x * x); return x * sigmoidf_(2.f * u); }
; __device__ __forceinline__ void lru_scan(unsigned char* ws, int unit, int wave, int tid_, LAS float* sm) {
;     ...
;     for (int t = 0; t < 512; t += 16) {
;         bf16_t la[16], uu[16], gg[16];
; #pragma unroll
;         for (int k = 0; k < 16; ++k) { la[k] = lap[(size_t)(t + k) * 512]; uu[k] = up[(size_t)(t + k) * 2048]; gg[k] = gp[(size_t)(t + k) * 1024]; }
; #pragma unroll
;         for (int k = 0; k < 16; ++k) { const float a = __expf(bf2f(la[k])); hcar = a * hcar + bf2f(uu[k]); up[(size_t)(t + k) * 2048] = f2bf(bf2f(f2bf(hcar)) * gelu_tanh(bf2f(gg[k]))); }
;     }
	v_add_f32_e32 v122, 1.0, v122
	v_add_f32_e32 v123, 1.0, v123
	v_rcp_f32_e32 v108, v108
	v_rcp_f32_e32 v109, v109
	v_rcp_f32_e32 v110, v110
	v_rcp_f32_e32 v111, v111
	v_rcp_f32_e32 v112, v112
	v_rcp_f32_e32 v113, v113
	v_rcp_f32_e32 v114, v114
	v_rcp_f32_e32 v115, v115
	v_rcp_f32_e32 v116, v116
	v_rcp_f32_e32 v117, v117
	v_rcp_f32_e32 v118, v118
	v_rcp_f32_e32 v119, v119
	v_rcp_f32_e32 v120, v120
	v_rcp_f32_e32 v121, v121
	v_rcp_f32_e32 v122, v122
	v_rcp_f32_e32 v123, v123
	v_mul_f32_e32 v108, v108, v84
	v_mul_f32_e32 v109, v109, v85
	v_mul_f32_e32 v110, v110, v86
	v_mul_f32_e32 v111, v111, v87
	v_mul_f32_e32 v112, v112, v88
	v_mul_f32_e32 v113, v113, v89
	v_mul_f32_e32 v114, v114, v90
	v_mul_f32_e32 v115, v115, v91
	v_mul_f32_e32 v116, v116, v92
	v_mul_f32_e32 v117, v117, v93
	v_mul_f32_e32 v118, v118, v94
	v_mul_f32_e32 v119, v119, v95
	v_mul_f32_e32 v120, v120, v96
	v_mul_f32_e32 v121, v121, v97
	v_mul_f32_e32 v122, v122, v98
	v_mul_f32_e32 v123, v123, v99
	v_fma_f32 v4, v32, v4, v48
	v_cvt_pk_bf16_f32 v48, v4, v1
	v_fma_f32 v4, v33, v4, v49
	v_cvt_pk_bf16_f32 v49, v4, v1
	v_fma_f32 v4, v34, v4, v50
	v_cvt_pk_bf16_f32 v50, v4, v1
	v_fma_f32 v4, v35, v4, v51
	v_cvt_pk_bf16_f32 v51, v4, v1
	v_fma_f32 v4, v36, v4, v52
	v_cvt_pk_bf16_f32 v52, v4, v1
	v_fma_f32 v4, v37, v4, v53
	v_cvt_pk_bf16_f32 v53, v4, v1
	v_fma_f32 v4, v38, v4, v54
	v_cvt_pk_bf16_f32 v54, v4, v1
	v_fma_f32 v4, v39, v4, v55
	v_cvt_pk_bf16_f32 v55, v4, v1
	v_fma_f32 v4, v40, v4, v56
	v_cvt_pk_bf16_f32 v56, v4, v1
	v_fma_f32 v4, v41, v4, v57
	v_cvt_pk_bf16_f32 v57, v4, v1
	v_fma_f32 v4, v42, v4, v58
	v_cvt_pk_bf16_f32 v58, v4, v1
	v_fma_f32 v4, v43, v4, v59
	v_cvt_pk_bf16_f32 v59, v4, v1
	v_fma_f32 v4, v44, v4, v60
	v_cvt_pk_bf16_f32 v60, v4, v1
	v_fma_f32 v4, v45, v4, v61
	v_cvt_pk_bf16_f32 v61, v4, v1
	v_fma_f32 v4, v46, v4, v62
	v_cvt_pk_bf16_f32 v62, v4, v1
	v_fma_f32 v4, v47, v4, v63
	v_cvt_pk_bf16_f32 v63, v4, v1
	v_lshlrev_b32_e32 v48, 16, v48
	v_lshlrev_b32_e32 v49, 16, v49
	v_lshlrev_b32_e32 v50, 16, v50
	v_lshlrev_b32_e32 v51, 16, v51
	v_lshlrev_b32_e32 v52, 16, v52
	v_lshlrev_b32_e32 v53, 16, v53
	v_lshlrev_b32_e32 v54, 16, v54
	v_lshlrev_b32_e32 v55, 16, v55
	v_lshlrev_b32_e32 v56, 16, v56
	v_lshlrev_b32_e32 v57, 16, v57
	v_lshlrev_b32_e32 v58, 16, v58
	v_lshlrev_b32_e32 v59, 16, v59
	v_lshlrev_b32_e32 v60, 16, v60
	v_lshlrev_b32_e32 v61, 16, v61
	v_lshlrev_b32_e32 v62, 16, v62
	v_lshlrev_b32_e32 v63, 16, v63
	v_mul_f32_e32 v48, v108, v48
	v_mul_f32_e32 v49, v109, v49
	v_mul_f32_e32 v50, v110, v50
	v_mul_f32_e32 v51, v111, v51
	v_mul_f32_e32 v52, v112, v52
	v_mul_f32_e32 v53, v113, v53
	v_mul_f32_e32 v54, v114, v54
	v_mul_f32_e32 v55, v115, v55
	v_mul_f32_e32 v56, v116, v56
	v_mul_f32_e32 v57, v117, v57
	v_mul_f32_e32 v58, v118, v58
	v_mul_f32_e32 v59, v119, v59
	v_mul_f32_e32 v60, v120, v60
	v_mul_f32_e32 v61, v121, v61
	v_mul_f32_e32 v62, v122, v62
	v_mul_f32_e32 v63, v123, v63
	v_cvt_pk_bf16_f32 v48, v48, v1
	v_cvt_pk_bf16_f32 v49, v49, v1
	v_cvt_pk_bf16_f32 v50, v50, v1
	v_cvt_pk_bf16_f32 v51, v51, v1
	v_cvt_pk_bf16_f32 v52, v52, v1
	v_cvt_pk_bf16_f32 v53, v53, v1
	v_cvt_pk_bf16_f32 v54, v54, v1
	v_cvt_pk_bf16_f32 v55, v55, v1
	v_cvt_pk_bf16_f32 v56, v56, v1
	v_cvt_pk_bf16_f32 v57, v57, v1
	v_cvt_pk_bf16_f32 v58, v58, v1
	v_cvt_pk_bf16_f32 v59, v59, v1
	v_cvt_pk_bf16_f32 v60, v60, v1
	v_cvt_pk_bf16_f32 v61, v61, v1
	v_cvt_pk_bf16_f32 v62, v62, v1
	v_cvt_pk_bf16_f32 v63, v63, v1
	global_store_short v68, v48, s[6:7] offset:3072
	global_store_short v69, v49, s[6:7] offset:3072
	global_store_short v70, v50, s[6:7] offset:3072
	global_store_short v71, v51, s[6:7] offset:3072
	global_store_short v72, v52, s[6:7] offset:3072
	global_store_short v73, v53, s[6:7] offset:3072
	global_store_short v74, v54, s[6:7] offset:3072
	global_store_short v75, v55, s[6:7] offset:3072
	global_store_short v76, v56, s[6:7] offset:3072
	global_store_short v77, v57, s[6:7] offset:3072
	global_store_short v78, v58, s[6:7] offset:3072
	global_store_short v79, v59, s[6:7] offset:3072
	global_store_short v80, v60, s[6:7] offset:3072
	global_store_short v81, v61, s[6:7] offset:3072
	global_store_short v82, v62, s[6:7] offset:3072
	global_store_short v83, v63, s[6:7] offset:3072
	s_add_u32 s6, s6, 0x10000
	s_addc_u32 s7, s7, 0
	s_add_u32 s0, s0, 0x8000
	s_addc_u32 s1, s1, 0
	s_add_u32 s8, s8, 0x4000
	s_addc_u32 s9, s9, 0
	s_add_i32 s10, s10, 16
	s_cmpk_lt_u32 s10, 0x1f0
	s_cbranch_scc1 .LBB0_1219
	s_barrier
